# lean scan loader (incremental per-thread pointers), weight-conversion tasks moved off the 24 four-unit workgroups, scan-step reads spread over DPP gaps, PREP_EARLY 512->256 (one early tile per workgro
# speedup vs baseline: 1.0124x; 1.0124x over previous
.LBB0_275:
	s_and_b64 vcc, exec, s[24:25]
	s_cbranch_vccz .LBB0_1279
	s_cmpk_gt_i32 s30, 0x7f
	s_mov_b64 s[24:25], -1
	s_cbranch_scc0 .LBB0_1047
	s_add_i32 s80, s36, 0xffffff80
	s_cmpk_gt_u32 s30, 0x3bf
	s_cbranch_scc1 .LBB0_942
	s_add_i32 s38, s30, 0x80
	s_add_i32 s2, s30, 64
	s_lshr_b32 s2, s2, 3
	s_lshl_b32 s3, s38, 8
	s_and_b32 s3, s3, 0x300
	s_and_b32 s24, s30, 4
	s_sub_i32 s25, 0xff, s2
	s_cmp_eq_u32 s24, 0
	s_cselect_b32 s2, s2, s25
	s_or_b32 s2, s2, s3
	s_waitcnt vmcnt(0)
	v_mov_b32_e32 v4, v232
	s_lshl_b32 s31, s2, 4
	s_mov_b32 s2, 0x38e38e39
	s_nop 0
	v_mul_hi_i32 v0, v4, s2
	v_lshrrev_b32_e32 v2, 31, v0
	v_ashrrev_i32_e32 v0, 6, v0
	v_add_u32_e32 v3, v0, v2
	s_movk_i32 s2, 0xfee0
	v_mad_i32_i24 v0, v3, s2, v4
	v_readlane_b32 s2, v252, 18
	v_readlane_b32 s3, v252, 19
	v_lshlrev_b32_e32 v2, 2, v0
	v_add_u32_e32 v5, s31, v3
	v_mov_b64_e32 v[6:7], s[2:3]
	s_movk_i32 s2, 0x900
	v_mad_i64_i32 v[6:7], s[24:25], v5, s2, v[6:7]
	v_ashrrev_i32_e32 v3, 31, v2
	v_lshl_add_u64 v[6:7], v[2:3], 1, v[6:7]
	global_load_dwordx2 v[58:59], v[6:7], off
	s_movk_i32 s2, 0x3fff
	v_cmp_lt_i32_e64 s[42:43], s2, v5
	s_movk_i32 s2, 0x5f
	v_cmp_lt_i32_e32 vcc, s2, v0
	s_and_saveexec_b64 s[26:27], s[42:43]
	s_xor_b64 s[26:27], exec, s[26:27]
	s_cbranch_execz .LBB0_284
	s_and_saveexec_b64 s[24:25], vcc
	s_xor_b64 s[24:25], exec, s[24:25]
	v_add_u32_e32 v0, 0xfffffe80, v2
	s_mov_b32 s2, 0xaaaaaaab
	v_mul_hi_u32 v0, v0, s2
	v_lshrrev_b32_e32 v6, 8, v0
	s_andn2_saveexec_b64 s[24:25], s[24:25]
	s_mov_b32 s2, 0x2aaaaaab
	v_mul_hi_i32 v0, v0, s2
	v_lshrrev_b32_e32 v6, 31, v0
	v_ashrrev_i32_e32 v0, 3, v0
	v_add_u32_e32 v6, v0, v6
	s_or_b64 exec, exec, s[24:25]
	v_cmp_eq_u32_e64 s[42:43], 0, v6
	s_nop 1
	v_cndmask_b32_e64 v0, v239, 0, s[42:43]
	v_cmp_ne_u32_sdwa s[24:25], v5, v0 src0_sel:BYTE_0 src1_sel:DWORD
	v_cndmask_b32_e64 v6, 1, -1, s[42:43]

.LBB0_936:
	v_or_b32_e32 v0, s26, v94
	v_lshlrev_b32_e32 v114, 2, v0
	v_lshl_or_b32 v146, v0, 4, v95
	v_ashrrev_i32_e32 v115, 31, v114
	v_ashrrev_i32_e32 v147, 31, v146
	v_lshlrev_b64 v[114:115], 10, v[114:115]
	v_lshlrev_b64 v[188:189], 2, v[146:147]
	v_lshl_add_u64 v[114:115], v[96:97], 0, v[114:115]
	v_lshl_add_u64 v[54:55], s[86:87], 0, v[188:189]
	v_add_co_u32_e32 v126, vcc, s3, v114
	v_lshl_add_u32 v50, v146, 2, v108
	global_load_dwordx4 v[110:113], v[54:55], off
	v_lshl_add_u64 v[54:55], s[84:85], 0, v[188:189]
	v_addc_co_u32_e32 v127, vcc, 0, v115, vcc
	ds_read_b128 v[50:53], v50 offset:1536
	global_load_dwordx4 v[54:57], v[54:55], off
	s_nop 0
	global_load_dwordx4 v[114:117], v[126:127], off
	global_load_dwordx4 v[118:121], v[126:127], off offset:1024
	global_load_dwordx4 v[122:125], v[126:127], off offset:2048
	s_nop 0
	global_load_dwordx4 v[126:129], v[126:127], off offset:3072
	v_lshlrev_b32_e32 v172, 1, v0
	v_ashrrev_i32_e32 v173, 31, v172
	v_lshlrev_b64 v[130:131], 10, v[172:173]
	v_lshl_add_u64 v[168:169], v[96:97], 0, v[130:131]
	global_load_dwordx4 v[130:133], v[168:169], off
	v_or_b32_e32 v138, 1, v172
	v_ashrrev_i32_e32 v139, 31, v138
	v_add_co_u32_e32 v142, vcc, s20, v168
	v_lshlrev_b64 v[138:139], 10, v[138:139]
	s_nop 0
	v_addc_co_u32_e32 v143, vcc, 0, v169, vcc
	v_lshl_add_u64 v[138:139], v[96:97], 0, v[138:139]
	global_load_dwordx4 v[134:137], v[142:143], off
	s_nop 0
	global_load_dwordx4 v[138:141], v[138:139], off
	s_nop 0
	global_load_dwordx4 v[142:145], v[142:143], off offset:1024
	v_lshl_add_u64 v[180:181], s[88:89], 0, v[188:189]
	global_load_dwordx4 v[156:159], v[180:181], off
	v_lshl_add_u64 v[184:185], s[0:1], 0, v[188:189]
	global_load_dwordx4 v[160:163], v[184:185], off
	v_add_co_u32_e32 v164, vcc, s22, v168
	v_add_u32_e32 v172, 33, v172
	s_nop 0
	v_addc_co_u32_e32 v165, vcc, 0, v169, vcc
	v_ashrrev_i32_e32 v173, 31, v172
	v_add_co_u32_e32 v176, vcc, s2, v168
	v_lshlrev_b64 v[172:173], 10, v[172:173]
	s_nop 0
	v_addc_co_u32_e32 v177, vcc, 0, v169, vcc
	v_lshl_add_u64 v[172:173], v[96:97], 0, v[172:173]
	global_load_dwordx4 v[164:167], v[164:165], off
	s_mov_b32 s26, 1
	global_load_dwordx4 v[168:171], v[176:177], off
	s_nop 0
	global_load_dwordx4 v[172:175], v[172:173], off
	s_nop 0
	global_load_dwordx4 v[176:179], v[176:177], off offset:1024
	s_nop 0
	global_load_dwordx4 v[180:183], v[180:181], off offset:1024
	s_nop 0
	global_load_dwordx4 v[184:187], v[184:185], off offset:1024
	s_and_b64 vcc, exec, s[34:35]
	s_mov_b64 s[34:35], 0
	s_waitcnt vmcnt(15)
	v_mfma_f32_16x16x32_bf16 v[114:117], v[114:117], v[2:5], 0
	s_waitcnt lgkmcnt(0)
	v_pk_mul_f32 v[110:111], v[50:51], v[110:111]
	v_pk_mul_f32 v[112:113], v[52:53], v[112:113]
	s_waitcnt vmcnt(14)
	v_mfma_f32_16x16x32_bf16 v[114:117], v[118:121], v[6:9], v[114:117]
	s_waitcnt vmcnt(13)
	v_mfma_f32_16x16x32_bf16 v[114:117], v[122:125], v[10:13], v[114:117]
	v_lshlrev_b64 v[122:123], 1, v[146:147]
	v_pk_mul_f32 v[124:125], v[110:111], v[100:101]
	s_waitcnt vmcnt(12)
	v_mfma_f32_16x16x32_bf16 v[114:117], v[126:129], v[14:17], v[114:117]
	v_mul_f32_e64 v128, v112, v100
	v_mul_f32_e64 v129, v113, v101
	s_waitcnt vmcnt(10)
	v_mfma_f32_16x16x32_bf16 v[118:121], v[134:137], v[22:25], 0
	s_nop 3
	v_cvt_pk_bf16_f32 v114, v114, v115
	v_cvt_pk_bf16_f32 v115, v116, v117
	v_lshl_add_u64 v[116:117], v[98:99], 0, v[122:123]
	global_store_dwordx2 v[116:117], v[114:115], off
	v_mfma_f32_16x16x32_bf16 v[114:117], v[130:133], v[18:21], 0
	v_lshl_add_u64 v[130:131], v[104:105], 0, v[188:189]
	s_waitcnt vmcnt(10)
	v_mfma_f32_16x16x32_bf16 v[114:117], v[138:141], v[26:29], v[114:117]
	s_waitcnt vmcnt(9)
	v_mfma_f32_16x16x32_bf16 v[118:121], v[142:145], v[30:33], v[118:121]
	s_waitcnt vmcnt(8)
	s_nop 4
	v_add_f32_e32 v0, v156, v114
	v_mul_f32_e32 v0, 0xbfb8aa3b, v0
	v_exp_f32_e32 v0, v0
	s_nop 0
	v_add_f32_e32 v0, 1.0, v0
	v_rcp_f32_e32 v0, v0
	s_nop 0
	v_mul_f32_e32 v0, 0xbf1b4598, v0
	v_mul_f32_e32 v0, 0x3fb8aa3b, v0
	v_exp_f32_e32 v114, v0
	s_waitcnt vmcnt(7)
	v_add_f32_e32 v0, v160, v118
	v_mul_f32_e32 v0, 0xbfb8aa3b, v0
	v_exp_f32_e32 v0, v0
	s_nop 0
	v_add_f32_e32 v0, 1.0, v0
	v_rcp_f32_e32 v118, v0
	v_add_f32_e32 v0, v157, v115
	v_mul_f32_e32 v0, 0xbfb8aa3b, v0
	v_exp_f32_e32 v0, v0
	s_nop 0
	v_add_f32_e32 v0, 1.0, v0
	v_rcp_f32_e32 v0, v0
	s_nop 0
	v_mul_f32_e32 v0, 0xbf1b4598, v0
	v_mul_f32_e32 v0, 0x3fb8aa3b, v0
	v_exp_f32_e32 v115, v0
	v_add_f32_e32 v0, v161, v119
	v_mul_f32_e32 v0, 0xbfb8aa3b, v0
	v_exp_f32_e32 v0, v0
	s_nop 0
	v_add_f32_e32 v0, 1.0, v0
	v_rcp_f32_e32 v119, v0
	v_add_f32_e32 v0, v158, v116
	v_mul_f32_e32 v0, 0xbfb8aa3b, v0
	v_exp_f32_e32 v0, v0
	v_pk_add_f32 v[110:111], v[118:119], -1.0 op_sel_hi:[1,0]
	v_add_f32_e32 v0, 1.0, v0
	v_rcp_f32_e32 v0, v0
	v_pk_fma_f32 v[110:111], v[54:55], v[110:111], 1.0 op_sel_hi:[1,1,0]
	v_mul_f32_e32 v0, 0xbf1b4598, v0
	v_mul_f32_e32 v0, 0x3fb8aa3b, v0
	v_exp_f32_e32 v116, v0
	v_add_f32_e32 v0, v162, v120
	v_mul_f32_e32 v0, 0xbfb8aa3b, v0
	v_exp_f32_e32 v0, v0
	v_pk_mul_f32 v[126:127], v[50:51], v[110:111]
	v_pk_mul_f32 v[110:111], v[124:125], v[118:119]
	v_add_f32_e32 v0, 1.0, v0
	v_rcp_f32_e32 v120, v0
	v_add_f32_e32 v0, v159, v117
	v_mul_f32_e32 v0, 0xbfb8aa3b, v0
	v_exp_f32_e32 v0, v0
	s_nop 0
	v_add_f32_e32 v0, 1.0, v0
	v_rcp_f32_e32 v0, v0
	s_nop 0
	v_mul_f32_e32 v0, 0xbf1b4598, v0
	v_mul_f32_e32 v0, 0x3fb8aa3b, v0
	v_exp_f32_e32 v117, v0
	v_add_f32_e32 v0, v163, v121
	v_mul_f32_e32 v0, 0xbfb8aa3b, v0
	v_exp_f32_e32 v0, v0
	s_nop 0
	v_add_f32_e32 v0, 1.0, v0
	v_rcp_f32_e32 v121, v0
	s_nop 0
	v_pk_add_f32 v[118:119], v[120:121], -1.0 op_sel_hi:[1,0]
	s_nop 0
	v_pk_fma_f32 v[118:119], v[56:57], v[118:119], 1.0 op_sel_hi:[1,1,0]
	v_pk_mul_f32 v[112:113], v[128:129], v[120:121]
	v_pk_mul_f32 v[118:119], v[52:53], v[118:119]
	v_lshl_add_u64 v[120:121], v[102:103], 0, v[188:189]
	global_store_dwordx4 v[130:131], v[110:113], off
	global_store_dwordx4 v[120:121], v[114:117], off
	s_nop 0
	v_cvt_pk_bf16_f32 v110, v126, v127
	v_cvt_pk_bf16_f32 v111, v118, v119
	v_lshl_add_u64 v[118:119], v[106:107], 0, v[122:123]
	global_store_dwordx2 v[118:119], v[110:111], off
	s_waitcnt vmcnt(9)
	v_mfma_f32_16x16x32_bf16 v[110:113], v[164:167], v[34:37], 0
	s_waitcnt vmcnt(7)
	v_mfma_f32_16x16x32_bf16 v[110:113], v[172:175], v[42:45], v[110:113]
	v_mfma_f32_16x16x32_bf16 v[114:117], v[168:171], v[38:41], 0
	s_waitcnt vmcnt(6)
	v_mfma_f32_16x16x32_bf16 v[114:117], v[176:179], v[46:49], v[114:117]
	s_waitcnt vmcnt(5)
	s_nop 3
	v_add_f32_e32 v0, v180, v110
	v_mul_f32_e32 v0, 0xbfb8aa3b, v0
	v_exp_f32_e32 v0, v0
	s_nop 0
	v_add_f32_e32 v0, 1.0, v0
	v_rcp_f32_e32 v0, v0
	s_nop 0
	v_mul_f32_e32 v0, 0xbf1b4598, v0
	v_mul_f32_e32 v0, 0x3fb8aa3b, v0
	v_exp_f32_e32 v110, v0
	s_waitcnt vmcnt(4)
	v_add_f32_e32 v0, v184, v114
	v_mul_f32_e32 v0, 0xbfb8aa3b, v0
	v_exp_f32_e32 v0, v0
	s_nop 0
	v_add_f32_e32 v0, 1.0, v0
	v_rcp_f32_e32 v114, v0
	v_add_f32_e32 v0, v181, v111
	v_mul_f32_e32 v0, 0xbfb8aa3b, v0
	v_exp_f32_e32 v0, v0
	s_nop 0
	v_add_f32_e32 v0, 1.0, v0
	v_rcp_f32_e32 v0, v0
	s_nop 0
	v_mul_f32_e32 v0, 0xbf1b4598, v0
	v_mul_f32_e32 v0, 0x3fb8aa3b, v0
	v_exp_f32_e32 v111, v0
	v_add_f32_e32 v0, v185, v115
	v_mul_f32_e32 v0, 0xbfb8aa3b, v0
	v_exp_f32_e32 v0, v0
	s_nop 0
	v_add_f32_e32 v0, 1.0, v0
	v_rcp_f32_e32 v115, v0
	v_add_f32_e32 v0, v182, v112
	v_mul_f32_e32 v0, 0xbfb8aa3b, v0
	v_exp_f32_e32 v0, v0
	v_pk_add_f32 v[122:123], v[114:115], -1.0 op_sel_hi:[1,0]
	v_pk_mul_f32 v[114:115], v[124:125], v[114:115]
	v_pk_fma_f32 v[54:55], v[54:55], v[122:123], 1.0 op_sel_hi:[1,1,0]
	v_add_f32_e32 v0, 1.0, v0
	v_rcp_f32_e32 v0, v0
	v_pk_mul_f32 v[50:51], v[50:51], v[54:55]
	v_mul_f32_e32 v0, 0xbf1b4598, v0
	v_mul_f32_e32 v0, 0x3fb8aa3b, v0
	v_exp_f32_e32 v112, v0
	v_add_f32_e32 v0, v186, v116
	v_mul_f32_e32 v0, 0xbfb8aa3b, v0
	v_exp_f32_e32 v0, v0
	v_cvt_pk_bf16_f32 v50, v50, v51
	v_add_f32_e32 v0, 1.0, v0
	v_rcp_f32_e32 v54, v0
	v_add_f32_e32 v0, v183, v113
	v_mul_f32_e32 v0, 0xbfb8aa3b, v0
	v_exp_f32_e32 v0, v0
	s_nop 0
	v_add_f32_e32 v0, 1.0, v0
	v_rcp_f32_e32 v0, v0
	s_nop 0
	v_mul_f32_e32 v0, 0xbf1b4598, v0
	v_mul_f32_e32 v0, 0x3fb8aa3b, v0
	v_exp_f32_e32 v113, v0
	v_add_f32_e32 v0, v187, v117
	v_mul_f32_e32 v0, 0xbfb8aa3b, v0
	v_exp_f32_e32 v0, v0
	s_nop 0
	v_add_f32_e32 v0, 1.0, v0
	v_rcp_f32_e32 v55, v0
	s_nop 0
	v_pk_mul_f32 v[116:117], v[128:129], v[54:55]
	v_pk_add_f32 v[54:55], v[54:55], -1.0 op_sel_hi:[1,0]
	global_store_dwordx4 v[120:121], v[110:113], off offset:1024
	global_store_dwordx4 v[130:131], v[114:117], off offset:1024
	v_pk_fma_f32 v[54:55], v[56:57], v[54:55], 1.0 op_sel_hi:[1,1,0]
	s_nop 0
	v_pk_mul_f32 v[52:53], v[52:53], v[54:55]
	s_nop 0
	v_cvt_pk_bf16_f32 v51, v52, v53
	global_store_dwordx2 v[118:119], v[50:51], off offset:512
	s_cbranch_vccnz .LBB0_936
	s_barrier
	s_waitcnt vmcnt(0)
	v_readlane_b32 s2, v251, 40
	v_readlane_b32 s3, v251, 41
	s_barrier
	s_and_saveexec_b64 s[26:27], s[2:3]
	s_cbranch_execz .LBB0_531
	s_mov_b64 s[34:35], exec
	v_mbcnt_lo_u32_b32 v0, s34, 0
	buffer_wbl2 sc1
	s_waitcnt vmcnt(0)
	s_waitcnt vmcnt(0)
	v_mbcnt_hi_u32_b32 v0, s35, v0
	v_cmp_eq_u32_e32 vcc, 0, v0
	s_and_b64 s[42:43], exec, vcc
	s_mov_b64 exec, s[42:43]
	s_cbranch_execz .LBB0_531
	s_addk_i32 s31, 0xff00
	s_ashr_i32 s2, s31, 31
	v_readlane_b32 s3, v249, 36
	s_xor_b32 s2, s2, s3
	s_abs_i32 s3, s31
	v_readlane_b32 s4, v249, 37
	s_mul_hi_u32 s31, s3, s4
	s_mul_i32 s33, s31, s37
	s_sub_i32 s3, s3, s33
	s_add_i32 s33, s31, 1
	s_sub_i32 s42, s3, s37
	s_cmp_ge_u32 s3, s37
	s_cselect_b32 s31, s33, s31
	s_cselect_b32 s3, s42, s3
	s_add_i32 s33, s31, 1
	s_cmp_ge_u32 s3, s37
	s_cselect_b32 s3, s33, s31
	s_xor_b32 s3, s3, s2
	s_sub_i32 s2, s3, s2
	s_lshl_b32 s42, s2, 6
	s_ashr_i32 s43, s42, 31
	s_lshl_b64 s[42:43], s[42:43], 2
	v_readlane_b32 s2, v250, 56
	s_add_u32 s42, s2, s42
	v_readlane_b32 s2, v250, 57
	s_addc_u32 s43, s2, s43
	s_bcnt1_i32_b64 s2, s[34:35]
	v_mov_b32_e32 v0, s2
	global_atomic_add v1, v0, s[42:43]
	s_branch .LBB0_531

.LBB0_1000:
	v_readlane_b32 s2, v250, 19
	v_readlane_b32 s3, v250, 20
	s_and_b64 vcc, exec, s[2:3]
	s_cbranch_vccz .LBB0_1046
	s_cmp_lt_i32 s48, 24
	s_cbranch_scc1 .LBB0_1046
	s_sub_i32 s48, s48, 24
	s_sub_i32 s30, s30, 24
	s_movk_i32 s80, 0x68
	s_movk_i32 s36, 0xe8
	s_cmpk_gt_i32 s30, 0xc3f
	s_cbranch_scc1 .LBB0_1039
	s_and_b32 s27, s30, 15
	s_lshl_b32 s46, s48, 2
	s_cmpk_gt_i32 s30, 0x2ff
	v_mov_b32_e32 v0, v232
	s_mov_b64 s[44:45], -1
	s_cbranch_scc0 .LBB0_1005
	s_cmpk_lt_u32 s48, 0x380
	s_cbranch_scc1 .LBB0_2209
	s_cmpk_lt_u32 s48, 0x900
	s_cselect_b64 s[42:43], -1, 0
	s_add_i32 s2, s48, 0xf700
	s_and_b32 s3, s2, 0xffff
	s_mul_i32 s3, s3, 0xba2f
	s_lshr_b32 s3, s3, 21
	s_mul_i32 s24, s3, 44
	s_sub_i32 s2, s2, s24
	s_and_b32 s24, s46, 0x3fc0
	s_add_i32 s26, s24, 0xfffff200
	s_bfe_i32 s25, s30, 0x10005
	s_lshr_b32 s31, s26, 1
	s_and_b32 s25, s25, 0xb00
	s_and_b32 s31, s31, 0x7fffff80
	s_and_b32 s24, s46, 64
	s_add_i32 s31, s31, s25
	s_and_b32 s2, s2, 0xffff
	s_lshl_b32 s3, s3, 6
	s_or_b32 s44, s31, s24
	s_and_b64 s[24:25], s[42:43], exec
	v_readlane_b32 s4, v249, 3
	v_readlane_b32 s6, v249, 5
	v_readlane_b32 s5, v249, 4
	v_readlane_b32 s7, v249, 6
	s_mov_b32 s24, 0x700000
	s_cselect_b32 s35, s7, s5
	s_cselect_b32 s34, s6, s4
	s_cselect_b32 s24, s24, 0x1200000
	v_readlane_b32 s4, v249, 17
	v_readlane_b32 s5, v249, 18
	s_add_u32 s24, s4, s24
	s_addc_u32 s25, s5, 0
	s_and_b64 s[42:43], s[42:43], exec
	s_movk_i32 s4, 0x1600
	s_movk_i32 s31, 0x400
	s_cselect_b32 s20, s4, 0x400
	s_cselect_b32 s33, s31, 0xb00
	s_cselect_b32 s37, s27, s2
	s_cselect_b32 s31, s26, s3
	s_cselect_b32 s26, s44, s3
	s_mov_b64 s[42:43], s[20:21]
	s_mov_b64 s[44:45], 0

.LBB0_1050:
	s_and_b32 s2, s26, 1
	s_mul_i32 s3, s2, 0x5400
	v_lshl_add_u32 v88, s2, 14, v87
	s_add_i32 s2, s3, 0
	v_add_u32_e32 v0, s2, v85
	v_add_u32_e32 v89, s2, v83
	ds_read_b128 v[14:17], v0 offset:20480
	ds_read_b128 v[10:13], v0 offset:20496
	ds_read_b128 v[6:9], v0 offset:20512
	ds_read_b128 v[2:5], v0 offset:20528
	ds_read_b128 v[62:65], v89
	ds_read_b128 v[46:49], v89 offset:256
	ds_read_b128 v[66:69], v89 offset:8192
	ds_read_b128 v[50:53], v89 offset:8448
	ds_read_b128 v[54:57], v89 offset:16384
	ds_read_b128 v[26:29], v89 offset:16640
	ds_read_b128 v[78:81], v89 offset:4096
	ds_read_b128 v[34:37], v89 offset:512
	ds_read_b128 v[58:61], v89 offset:4352
	ds_read_b128 v[30:33], v89 offset:4608
	ds_read_b128 v[70:73], v89 offset:12288
	ds_read_b128 v[38:41], v89 offset:8704
	ds_read_b128 v[42:45], v89 offset:12544
	ds_read_b128 v[22:25], v89 offset:12800
	ds_read_b128 v[18:21], v89 offset:16896
	s_waitcnt lgkmcnt(12)
	v_pk_mul_f32 v[66:67], v[74:75], v[66:67]
	s_waitcnt lgkmcnt(8)
	v_pk_mul_f32 v[78:79], v[14:15], v[78:79] op_sel_hi:[0,1]
	v_pk_fma_f32 v[66:67], v[76:77], v[68:69], v[66:67]
	v_pk_mul_f32 v[80:81], v[14:15], v[80:81] op_sel_hi:[0,1]
	v_add_f32_e32 v66, v66, v67
	v_pk_fma_f32 v[62:63], v[74:75], v[62:63], v[78:79]
	v_pk_fma_f32 v[64:65], v[76:77], v[64:65], v[80:81]
	v_add_f32_dpp v66, v66, v66 quad_perm:[1,0,3,2] row_mask:0xf bank_mask:0xf bound_ctrl:1
	v_mov_b32_e32 v0, v17
	v_mov_b32_e32 v82, v13
	v_add_f32_dpp v66, v66, v66 quad_perm:[2,3,0,1] row_mask:0xf bank_mask:0xf bound_ctrl:1
	v_mov_b32_e32 v84, v9
	v_mov_b32_e32 v86, v5
	v_add_f32_dpp v66, v66, v66 row_half_mirror row_mask:0xf bank_mask:0xf bound_ctrl:1
	s_add_i32 s26, s26, 1
	s_cmpk_eq_i32 s26, 0x110
	v_add_f32_dpp v66, v66, v66 row_ror:8 row_mask:0xf bank_mask:0xf bound_ctrl:1
	s_waitcnt lgkmcnt(4)
	v_pk_fma_f32 v[62:63], v[70:71], v[66:67], v[62:63] op_sel_hi:[1,0,1] neg_lo:[1,0,0] neg_hi:[1,0,0]
	v_pk_fma_f32 v[64:65], v[72:73], v[66:67], v[64:65] op_sel_hi:[1,0,1] neg_lo:[1,0,0] neg_hi:[1,0,0]
	v_pk_mul_f32 v[50:51], v[50:51], v[62:63]
	v_pk_mul_f32 v[46:47], v[46:47], v[62:63]
	v_pk_fma_f32 v[50:51], v[52:53], v[64:65], v[50:51]
	v_pk_fma_f32 v[66:67], v[14:15], v[58:59], v[46:47] op_sel:[1,0,0]
	v_add_f32_e32 v47, v50, v51
	v_pk_mul_f32 v[48:49], v[48:49], v[64:65]
	v_pk_mul_f32 v[56:57], v[56:57], v[64:65]
	v_add_f32_dpp v68, v47, v47 quad_perm:[1,0,3,2] row_mask:0xf bank_mask:0xf bound_ctrl:1
	v_pk_fma_f32 v[14:15], v[14:15], v[60:61], v[48:49] op_sel:[1,0,0]
	v_pk_fma_f32 v[54:55], v[54:55], v[62:63], v[56:57]
	v_add_f32_dpp v68, v68, v68 quad_perm:[2,3,0,1] row_mask:0xf bank_mask:0xf bound_ctrl:1
	v_add_f32_e32 v46, v54, v55
	ds_write_b32 v88, v46 offset:43008
	v_add_f32_dpp v68, v68, v68 row_half_mirror row_mask:0xf bank_mask:0xf bound_ctrl:1
	ds_read_b128 v[46:49], v89 offset:768
	ds_read_b128 v[50:53], v89 offset:4864
	ds_read_b128 v[54:57], v89 offset:8960
	ds_read_b128 v[58:61], v89 offset:13056
	ds_read_b128 v[62:65], v89 offset:17152
	v_add_f32_dpp v68, v68, v68 row_ror:8 row_mask:0xf bank_mask:0xf bound_ctrl:1
	s_waitcnt lgkmcnt(8)
	v_pk_fma_f32 v[42:43], v[42:43], v[68:69], v[66:67] op_sel_hi:[1,0,1] neg_lo:[1,0,0] neg_hi:[1,0,0]
	v_pk_fma_f32 v[14:15], v[44:45], v[68:69], v[14:15] op_sel_hi:[1,0,1] neg_lo:[1,0,0] neg_hi:[1,0,0]
	v_pk_mul_f32 v[38:39], v[38:39], v[42:43]
	v_pk_mul_f32 v[28:29], v[28:29], v[14:15]
	v_pk_mul_f32 v[36:37], v[36:37], v[14:15]
	v_pk_fma_f32 v[14:15], v[40:41], v[14:15], v[38:39]
	v_pk_mul_f32 v[34:35], v[34:35], v[42:43]
	v_add_f32_e32 v14, v14, v15
	v_pk_fma_f32 v[26:27], v[26:27], v[42:43], v[28:29]
	v_pk_fma_f32 v[42:43], v[16:17], v[30:31], v[34:35] op_sel_hi:[0,1,1]
	v_add_f32_dpp v66, v14, v14 quad_perm:[1,0,3,2] row_mask:0xf bank_mask:0xf bound_ctrl:1
	v_pk_fma_f32 v[44:45], v[16:17], v[32:33], v[36:37] op_sel_hi:[0,1,1]
	v_add_f32_e32 v16, v26, v27
	v_add_f32_dpp v66, v66, v66 quad_perm:[2,3,0,1] row_mask:0xf bank_mask:0xf bound_ctrl:1
	ds_write_b32 v88, v16 offset:44032
	ds_read_b128 v[14:17], v89 offset:1024
	ds_read_b128 v[26:29], v89 offset:5120
	ds_read_b128 v[30:33], v89 offset:9216
	ds_read_b128 v[34:37], v89 offset:13312
	ds_read_b128 v[38:41], v89 offset:17408
	v_add_f32_dpp v66, v66, v66 row_half_mirror row_mask:0xf bank_mask:0xf bound_ctrl:1
	s_nop 1
	v_add_f32_dpp v66, v66, v66 row_ror:8 row_mask:0xf bank_mask:0xf bound_ctrl:1
	s_waitcnt lgkmcnt(8)
	v_pk_fma_f32 v[22:23], v[22:23], v[66:67], v[42:43] op_sel_hi:[1,0,1] neg_lo:[1,0,0] neg_hi:[1,0,0]
	v_pk_fma_f32 v[24:25], v[24:25], v[66:67], v[44:45] op_sel_hi:[1,0,1] neg_lo:[1,0,0] neg_hi:[1,0,0]
	v_pk_mul_f32 v[42:43], v[54:55], v[22:23]
	v_pk_mul_f32 v[20:21], v[20:21], v[24:25]
	v_pk_mul_f32 v[44:45], v[46:47], v[22:23]
	v_pk_mul_f32 v[46:47], v[48:49], v[24:25]
	v_pk_fma_f32 v[18:19], v[18:19], v[22:23], v[20:21]
	v_pk_fma_f32 v[20:21], v[56:57], v[24:25], v[42:43]
	v_pk_fma_f32 v[54:55], v[0:1], v[50:51], v[44:45] op_sel_hi:[0,1,1]
	v_pk_fma_f32 v[56:57], v[0:1], v[52:53], v[46:47] op_sel_hi:[0,1,1]
	v_add_f32_e32 v0, v18, v19
	v_add_f32_e32 v18, v20, v21
	ds_write_b32 v88, v0 offset:45056
	s_nop 0
	v_add_f32_dpp v0, v18, v18 quad_perm:[1,0,3,2] row_mask:0xf bank_mask:0xf bound_ctrl:1
	ds_read_b128 v[18:21], v89 offset:1280
	ds_read_b128 v[22:25], v89 offset:5376
	v_add_f32_dpp v0, v0, v0 quad_perm:[2,3,0,1] row_mask:0xf bank_mask:0xf bound_ctrl:1
	ds_read_b128 v[42:45], v89 offset:9472
	ds_read_b128 v[46:49], v89 offset:13568
	v_add_f32_dpp v0, v0, v0 row_half_mirror row_mask:0xf bank_mask:0xf bound_ctrl:1
	ds_read_b128 v[50:53], v89 offset:17664
	s_nop 0
	v_add_f32_dpp v0, v0, v0 row_ror:8 row_mask:0xf bank_mask:0xf bound_ctrl:1
	s_waitcnt lgkmcnt(8)
	v_pk_fma_f32 v[54:55], v[58:59], v[0:1], v[54:55] op_sel_hi:[1,0,1] neg_lo:[1,0,0] neg_hi:[1,0,0]
	v_pk_fma_f32 v[56:57], v[60:61], v[0:1], v[56:57] op_sel_hi:[1,0,1] neg_lo:[1,0,0] neg_hi:[1,0,0]
	v_pk_mul_f32 v[30:31], v[30:31], v[54:55]
	v_pk_mul_f32 v[58:59], v[64:65], v[56:57]
	v_pk_mul_f32 v[14:15], v[14:15], v[54:55]
	v_pk_fma_f32 v[54:55], v[62:63], v[54:55], v[58:59]
	v_pk_fma_f32 v[30:31], v[32:33], v[56:57], v[30:31]
	v_pk_fma_f32 v[62:63], v[10:11], v[26:27], v[14:15] op_sel_hi:[0,1,1]
	v_add_f32_e32 v0, v54, v55
	v_add_f32_e32 v14, v30, v31
	ds_write_b32 v88, v0 offset:46080
	v_pk_mul_f32 v[16:17], v[16:17], v[56:57]
	v_add_f32_dpp v0, v14, v14 quad_perm:[1,0,3,2] row_mask:0xf bank_mask:0xf bound_ctrl:1
	v_pk_fma_f32 v[64:65], v[10:11], v[28:29], v[16:17] op_sel_hi:[0,1,1]
	ds_read_b128 v[14:17], v89 offset:1536
	v_add_f32_dpp v0, v0, v0 quad_perm:[2,3,0,1] row_mask:0xf bank_mask:0xf bound_ctrl:1
	ds_read_b128 v[26:29], v89 offset:5632
	ds_read_b128 v[30:33], v89 offset:9728
	v_add_f32_dpp v0, v0, v0 row_half_mirror row_mask:0xf bank_mask:0xf bound_ctrl:1
	ds_read_b128 v[54:57], v89 offset:13824
	ds_read_b128 v[58:61], v89 offset:17920
	v_add_f32_dpp v0, v0, v0 row_ror:8 row_mask:0xf bank_mask:0xf bound_ctrl:1
	s_waitcnt lgkmcnt(8)
	v_pk_fma_f32 v[34:35], v[34:35], v[0:1], v[62:63] op_sel_hi:[1,0,1] neg_lo:[1,0,0] neg_hi:[1,0,0]
	v_pk_fma_f32 v[36:37], v[36:37], v[0:1], v[64:65] op_sel_hi:[1,0,1] neg_lo:[1,0,0] neg_hi:[1,0,0]
	v_pk_mul_f32 v[42:43], v[42:43], v[34:35]
	v_pk_mul_f32 v[40:41], v[40:41], v[36:37]
	v_pk_mul_f32 v[18:19], v[18:19], v[34:35]
	v_pk_mul_f32 v[20:21], v[20:21], v[36:37]
	v_pk_fma_f32 v[34:35], v[38:39], v[34:35], v[40:41]
	v_pk_fma_f32 v[36:37], v[44:45], v[36:37], v[42:43]
	v_pk_fma_f32 v[62:63], v[10:11], v[22:23], v[18:19] op_sel:[1,0,0]
	v_add_f32_e32 v0, v34, v35
	v_add_f32_e32 v18, v36, v37
	ds_write_b32 v88, v0 offset:47104
	v_pk_fma_f32 v[10:11], v[10:11], v[24:25], v[20:21] op_sel:[1,0,0]
	v_add_f32_dpp v0, v18, v18 quad_perm:[1,0,3,2] row_mask:0xf bank_mask:0xf bound_ctrl:1
	ds_read_b128 v[18:21], v89 offset:1792
	ds_read_b128 v[22:25], v89 offset:5888
	v_add_f32_dpp v0, v0, v0 quad_perm:[2,3,0,1] row_mask:0xf bank_mask:0xf bound_ctrl:1
	ds_read_b128 v[34:37], v89 offset:9984
	ds_read_b128 v[38:41], v89 offset:14080
	v_add_f32_dpp v0, v0, v0 row_half_mirror row_mask:0xf bank_mask:0xf bound_ctrl:1
	ds_read_b128 v[42:45], v89 offset:18176
	s_nop 0
	v_add_f32_dpp v0, v0, v0 row_ror:8 row_mask:0xf bank_mask:0xf bound_ctrl:1
	s_waitcnt lgkmcnt(8)
	v_pk_fma_f32 v[46:47], v[46:47], v[0:1], v[62:63] op_sel_hi:[1,0,1] neg_lo:[1,0,0] neg_hi:[1,0,0]
	v_pk_fma_f32 v[10:11], v[48:49], v[0:1], v[10:11] op_sel_hi:[1,0,1] neg_lo:[1,0,0] neg_hi:[1,0,0]
	v_pk_mul_f32 v[30:31], v[30:31], v[46:47]
	v_pk_mul_f32 v[48:49], v[52:53], v[10:11]
	v_pk_mul_f32 v[14:15], v[14:15], v[46:47]
	v_pk_mul_f32 v[16:17], v[16:17], v[10:11]
	v_pk_fma_f32 v[46:47], v[50:51], v[46:47], v[48:49]
	v_pk_fma_f32 v[10:11], v[32:33], v[10:11], v[30:31]
	v_add_f32_e32 v0, v46, v47
	v_add_f32_e32 v10, v10, v11
	ds_write_b32 v88, v0 offset:48128
	v_pk_fma_f32 v[50:51], v[12:13], v[26:27], v[14:15] op_sel_hi:[0,1,1]
	v_add_f32_dpp v0, v10, v10 quad_perm:[1,0,3,2] row_mask:0xf bank_mask:0xf bound_ctrl:1
	v_pk_fma_f32 v[52:53], v[12:13], v[28:29], v[16:17] op_sel_hi:[0,1,1]
	ds_read_b128 v[10:13], v89 offset:2048
	v_add_f32_dpp v0, v0, v0 quad_perm:[2,3,0,1] row_mask:0xf bank_mask:0xf bound_ctrl:1
	ds_read_b128 v[14:17], v89 offset:6144
	ds_read_b128 v[26:29], v89 offset:10240
	v_add_f32_dpp v0, v0, v0 row_half_mirror row_mask:0xf bank_mask:0xf bound_ctrl:1
	ds_read_b128 v[30:33], v89 offset:14336
	ds_read_b128 v[46:49], v89 offset:18432
	v_add_f32_dpp v0, v0, v0 row_ror:8 row_mask:0xf bank_mask:0xf bound_ctrl:1
	s_waitcnt lgkmcnt(8)
	v_pk_fma_f32 v[50:51], v[54:55], v[0:1], v[50:51] op_sel_hi:[1,0,1] neg_lo:[1,0,0] neg_hi:[1,0,0]
	v_pk_fma_f32 v[52:53], v[56:57], v[0:1], v[52:53] op_sel_hi:[1,0,1] neg_lo:[1,0,0] neg_hi:[1,0,0]
	v_pk_mul_f32 v[34:35], v[34:35], v[50:51]
	v_pk_mul_f32 v[54:55], v[60:61], v[52:53]
	v_pk_mul_f32 v[18:19], v[18:19], v[50:51]
	v_pk_fma_f32 v[50:51], v[58:59], v[50:51], v[54:55]
	v_pk_fma_f32 v[34:35], v[36:37], v[52:53], v[34:35]
	v_pk_fma_f32 v[58:59], v[82:83], v[22:23], v[18:19] op_sel_hi:[0,1,1]
	v_add_f32_e32 v0, v50, v51
	v_add_f32_e32 v18, v34, v35
	ds_write_b32 v88, v0 offset:49152
	v_pk_mul_f32 v[20:21], v[20:21], v[52:53]
	v_add_f32_dpp v0, v18, v18 quad_perm:[1,0,3,2] row_mask:0xf bank_mask:0xf bound_ctrl:1
	v_pk_fma_f32 v[60:61], v[82:83], v[24:25], v[20:21] op_sel_hi:[0,1,1]
	ds_read_b128 v[18:21], v89 offset:2304
	v_add_f32_dpp v0, v0, v0 quad_perm:[2,3,0,1] row_mask:0xf bank_mask:0xf bound_ctrl:1
	ds_read_b128 v[22:25], v89 offset:6400
	ds_read_b128 v[34:37], v89 offset:10496
	v_add_f32_dpp v0, v0, v0 row_half_mirror row_mask:0xf bank_mask:0xf bound_ctrl:1
	ds_read_b128 v[50:53], v89 offset:14592
	ds_read_b128 v[54:57], v89 offset:18688
	v_add_f32_dpp v0, v0, v0 row_ror:8 row_mask:0xf bank_mask:0xf bound_ctrl:1
	s_waitcnt lgkmcnt(8)
	v_pk_fma_f32 v[38:39], v[38:39], v[0:1], v[58:59] op_sel_hi:[1,0,1] neg_lo:[1,0,0] neg_hi:[1,0,0]
	v_pk_fma_f32 v[40:41], v[40:41], v[0:1], v[60:61] op_sel_hi:[1,0,1] neg_lo:[1,0,0] neg_hi:[1,0,0]
	v_pk_mul_f32 v[26:27], v[26:27], v[38:39]
	v_pk_mul_f32 v[44:45], v[44:45], v[40:41]
	v_pk_mul_f32 v[10:11], v[10:11], v[38:39]
	v_pk_fma_f32 v[38:39], v[42:43], v[38:39], v[44:45]
	v_pk_fma_f32 v[26:27], v[28:29], v[40:41], v[26:27]
	v_pk_fma_f32 v[58:59], v[6:7], v[14:15], v[10:11] op_sel_hi:[0,1,1]
	v_add_f32_e32 v0, v38, v39
	v_add_f32_e32 v10, v26, v27
	ds_write_b32 v88, v0 offset:50176
	v_pk_mul_f32 v[12:13], v[12:13], v[40:41]
	v_add_f32_dpp v0, v10, v10 quad_perm:[1,0,3,2] row_mask:0xf bank_mask:0xf bound_ctrl:1
	v_pk_fma_f32 v[60:61], v[6:7], v[16:17], v[12:13] op_sel_hi:[0,1,1]
	ds_read_b128 v[10:13], v89 offset:2560
	v_add_f32_dpp v0, v0, v0 quad_perm:[2,3,0,1] row_mask:0xf bank_mask:0xf bound_ctrl:1
	ds_read_b128 v[14:17], v89 offset:6656
	ds_read_b128 v[26:29], v89 offset:10752
	v_add_f32_dpp v0, v0, v0 row_half_mirror row_mask:0xf bank_mask:0xf bound_ctrl:1
	ds_read_b128 v[38:41], v89 offset:14848
	ds_read_b128 v[42:45], v89 offset:18944
	v_add_f32_dpp v0, v0, v0 row_ror:8 row_mask:0xf bank_mask:0xf bound_ctrl:1
	s_waitcnt lgkmcnt(8)
	v_pk_fma_f32 v[30:31], v[30:31], v[0:1], v[58:59] op_sel_hi:[1,0,1] neg_lo:[1,0,0] neg_hi:[1,0,0]
	v_pk_fma_f32 v[32:33], v[32:33], v[0:1], v[60:61] op_sel_hi:[1,0,1] neg_lo:[1,0,0] neg_hi:[1,0,0]
	v_pk_mul_f32 v[34:35], v[34:35], v[30:31]
	v_pk_mul_f32 v[48:49], v[48:49], v[32:33]
	v_pk_mul_f32 v[18:19], v[18:19], v[30:31]
	v_pk_mul_f32 v[20:21], v[20:21], v[32:33]
	v_pk_fma_f32 v[30:31], v[46:47], v[30:31], v[48:49]
	v_pk_fma_f32 v[32:33], v[36:37], v[32:33], v[34:35]
	v_pk_fma_f32 v[58:59], v[6:7], v[22:23], v[18:19] op_sel:[1,0,0]
	v_add_f32_e32 v0, v30, v31
	v_add_f32_e32 v18, v32, v33
	ds_write_b32 v88, v0 offset:51200
	v_pk_fma_f32 v[6:7], v[6:7], v[24:25], v[20:21] op_sel:[1,0,0]
	v_add_f32_dpp v0, v18, v18 quad_perm:[1,0,3,2] row_mask:0xf bank_mask:0xf bound_ctrl:1
	ds_read_b128 v[18:21], v89 offset:2816
	ds_read_b128 v[22:25], v89 offset:6912
	v_add_f32_dpp v0, v0, v0 quad_perm:[2,3,0,1] row_mask:0xf bank_mask:0xf bound_ctrl:1
	ds_read_b128 v[30:33], v89 offset:11008
	ds_read_b128 v[34:37], v89 offset:15104
	v_add_f32_dpp v0, v0, v0 row_half_mirror row_mask:0xf bank_mask:0xf bound_ctrl:1
	ds_read_b128 v[46:49], v89 offset:19200
	s_nop 0
	v_add_f32_dpp v0, v0, v0 row_ror:8 row_mask:0xf bank_mask:0xf bound_ctrl:1
	s_waitcnt lgkmcnt(8)
	v_pk_fma_f32 v[50:51], v[50:51], v[0:1], v[58:59] op_sel_hi:[1,0,1] neg_lo:[1,0,0] neg_hi:[1,0,0]
	v_pk_fma_f32 v[6:7], v[52:53], v[0:1], v[6:7] op_sel_hi:[1,0,1] neg_lo:[1,0,0] neg_hi:[1,0,0]
	v_pk_mul_f32 v[26:27], v[26:27], v[50:51]
	v_pk_mul_f32 v[52:53], v[56:57], v[6:7]
	v_pk_mul_f32 v[10:11], v[10:11], v[50:51]
	v_pk_mul_f32 v[12:13], v[12:13], v[6:7]
	v_pk_fma_f32 v[50:51], v[54:55], v[50:51], v[52:53]
	v_pk_fma_f32 v[6:7], v[28:29], v[6:7], v[26:27]
	v_add_f32_e32 v0, v50, v51
	v_add_f32_e32 v6, v6, v7
	ds_write_b32 v88, v0 offset:52224
	v_pk_fma_f32 v[54:55], v[8:9], v[14:15], v[10:11] op_sel_hi:[0,1,1]
	v_add_f32_dpp v0, v6, v6 quad_perm:[1,0,3,2] row_mask:0xf bank_mask:0xf bound_ctrl:1
	v_pk_fma_f32 v[56:57], v[8:9], v[16:17], v[12:13] op_sel_hi:[0,1,1]
	ds_read_b128 v[6:9], v89 offset:3072
	v_add_f32_dpp v0, v0, v0 quad_perm:[2,3,0,1] row_mask:0xf bank_mask:0xf bound_ctrl:1
	ds_read_b128 v[10:13], v89 offset:7168
	ds_read_b128 v[14:17], v89 offset:11264
	v_add_f32_dpp v0, v0, v0 row_half_mirror row_mask:0xf bank_mask:0xf bound_ctrl:1
	ds_read_b128 v[26:29], v89 offset:15360
	ds_read_b128 v[50:53], v89 offset:19456
	v_add_f32_dpp v0, v0, v0 row_ror:8 row_mask:0xf bank_mask:0xf bound_ctrl:1
	s_waitcnt lgkmcnt(8)
	v_pk_fma_f32 v[38:39], v[38:39], v[0:1], v[54:55] op_sel_hi:[1,0,1] neg_lo:[1,0,0] neg_hi:[1,0,0]
	v_pk_fma_f32 v[40:41], v[40:41], v[0:1], v[56:57] op_sel_hi:[1,0,1] neg_lo:[1,0,0] neg_hi:[1,0,0]
	v_pk_mul_f32 v[30:31], v[30:31], v[38:39]
	v_pk_mul_f32 v[44:45], v[44:45], v[40:41]
	v_pk_mul_f32 v[18:19], v[18:19], v[38:39]
	v_pk_fma_f32 v[38:39], v[42:43], v[38:39], v[44:45]
	v_pk_fma_f32 v[30:31], v[32:33], v[40:41], v[30:31]
	v_pk_fma_f32 v[54:55], v[84:85], v[22:23], v[18:19] op_sel_hi:[0,1,1]
	v_add_f32_e32 v0, v38, v39
	v_add_f32_e32 v18, v30, v31
	ds_write_b32 v88, v0 offset:53248
	v_pk_mul_f32 v[20:21], v[20:21], v[40:41]
	v_add_f32_dpp v0, v18, v18 quad_perm:[1,0,3,2] row_mask:0xf bank_mask:0xf bound_ctrl:1
	v_pk_fma_f32 v[56:57], v[84:85], v[24:25], v[20:21] op_sel_hi:[0,1,1]
	ds_read_b128 v[18:21], v89 offset:3328
	v_add_f32_dpp v0, v0, v0 quad_perm:[2,3,0,1] row_mask:0xf bank_mask:0xf bound_ctrl:1
	ds_read_b128 v[22:25], v89 offset:7424
	ds_read_b128 v[30:33], v89 offset:11520
	v_add_f32_dpp v0, v0, v0 row_half_mirror row_mask:0xf bank_mask:0xf bound_ctrl:1
	ds_read_b128 v[38:41], v89 offset:15616
	ds_read_b128 v[42:45], v89 offset:19712
	v_add_f32_dpp v0, v0, v0 row_ror:8 row_mask:0xf bank_mask:0xf bound_ctrl:1
	s_waitcnt lgkmcnt(8)
	v_pk_fma_f32 v[34:35], v[34:35], v[0:1], v[54:55] op_sel_hi:[1,0,1] neg_lo:[1,0,0] neg_hi:[1,0,0]
	v_pk_fma_f32 v[36:37], v[36:37], v[0:1], v[56:57] op_sel_hi:[1,0,1] neg_lo:[1,0,0] neg_hi:[1,0,0]
	v_pk_mul_f32 v[14:15], v[14:15], v[34:35]
	v_pk_mul_f32 v[48:49], v[48:49], v[36:37]
	v_pk_mul_f32 v[6:7], v[6:7], v[34:35]
	v_pk_fma_f32 v[34:35], v[46:47], v[34:35], v[48:49]
	v_pk_fma_f32 v[14:15], v[16:17], v[36:37], v[14:15]
	v_pk_fma_f32 v[54:55], v[2:3], v[10:11], v[6:7] op_sel_hi:[0,1,1]
	v_add_f32_e32 v0, v34, v35
	v_add_f32_e32 v6, v14, v15
	ds_write_b32 v88, v0 offset:54272
	v_pk_mul_f32 v[8:9], v[8:9], v[36:37]
	v_add_f32_dpp v0, v6, v6 quad_perm:[1,0,3,2] row_mask:0xf bank_mask:0xf bound_ctrl:1
	v_pk_fma_f32 v[56:57], v[2:3], v[12:13], v[8:9] op_sel_hi:[0,1,1]
	ds_read_b128 v[6:9], v89 offset:3584
	v_add_f32_dpp v0, v0, v0 quad_perm:[2,3,0,1] row_mask:0xf bank_mask:0xf bound_ctrl:1
	ds_read_b128 v[10:13], v89 offset:7680
	ds_read_b128 v[14:17], v89 offset:11776
	v_add_f32_dpp v0, v0, v0 row_half_mirror row_mask:0xf bank_mask:0xf bound_ctrl:1
	ds_read_b128 v[34:37], v89 offset:15872
	ds_read_b128 v[46:49], v89 offset:19968
	v_add_f32_dpp v0, v0, v0 row_ror:8 row_mask:0xf bank_mask:0xf bound_ctrl:1
	s_waitcnt lgkmcnt(8)
	v_pk_fma_f32 v[26:27], v[26:27], v[0:1], v[54:55] op_sel_hi:[1,0,1] neg_lo:[1,0,0] neg_hi:[1,0,0]
	v_pk_fma_f32 v[28:29], v[28:29], v[0:1], v[56:57] op_sel_hi:[1,0,1] neg_lo:[1,0,0] neg_hi:[1,0,0]
	v_pk_mul_f32 v[30:31], v[30:31], v[26:27]
	v_pk_mul_f32 v[52:53], v[52:53], v[28:29]
	v_pk_mul_f32 v[18:19], v[18:19], v[26:27]
	v_pk_mul_f32 v[20:21], v[20:21], v[28:29]
	v_pk_fma_f32 v[26:27], v[50:51], v[26:27], v[52:53]
	v_pk_fma_f32 v[28:29], v[32:33], v[28:29], v[30:31]
	v_pk_fma_f32 v[54:55], v[2:3], v[22:23], v[18:19] op_sel:[1,0,0]
	v_add_f32_e32 v0, v26, v27
	v_add_f32_e32 v18, v28, v29
	ds_write_b32 v88, v0 offset:55296
	v_pk_fma_f32 v[2:3], v[2:3], v[24:25], v[20:21] op_sel:[1,0,0]
	v_add_f32_dpp v0, v18, v18 quad_perm:[1,0,3,2] row_mask:0xf bank_mask:0xf bound_ctrl:1
	ds_read_b128 v[18:21], v89 offset:3840
	ds_read_b128 v[22:25], v89 offset:7936
	v_add_f32_dpp v0, v0, v0 quad_perm:[2,3,0,1] row_mask:0xf bank_mask:0xf bound_ctrl:1
	ds_read_b128 v[26:29], v89 offset:12032
	ds_read_b128 v[30:33], v89 offset:16128
	v_add_f32_dpp v0, v0, v0 row_half_mirror row_mask:0xf bank_mask:0xf bound_ctrl:1
	ds_read_b128 v[50:53], v89 offset:20224
	s_nop 0
	v_add_f32_dpp v0, v0, v0 row_ror:8 row_mask:0xf bank_mask:0xf bound_ctrl:1
	s_waitcnt lgkmcnt(13)
	v_pk_fma_f32 v[38:39], v[38:39], v[0:1], v[54:55] op_sel_hi:[1,0,1] neg_lo:[1,0,0] neg_hi:[1,0,0]
	v_pk_fma_f32 v[2:3], v[40:41], v[0:1], v[2:3] op_sel_hi:[1,0,1] neg_lo:[1,0,0] neg_hi:[1,0,0]
	s_waitcnt lgkmcnt(8)
	v_pk_mul_f32 v[14:15], v[14:15], v[38:39]
	v_pk_mul_f32 v[40:41], v[44:45], v[2:3]
	v_pk_mul_f32 v[8:9], v[8:9], v[2:3]
	v_pk_fma_f32 v[2:3], v[16:17], v[2:3], v[14:15]
	v_pk_mul_f32 v[6:7], v[6:7], v[38:39]
	v_add_f32_e32 v0, v2, v3
	v_pk_fma_f32 v[6:7], v[4:5], v[10:11], v[6:7] op_sel_hi:[0,1,1]
	v_pk_fma_f32 v[4:5], v[4:5], v[12:13], v[8:9] op_sel_hi:[0,1,1]
	v_add_f32_dpp v0, v0, v0 quad_perm:[1,0,3,2] row_mask:0xf bank_mask:0xf bound_ctrl:1
	v_pk_fma_f32 v[38:39], v[42:43], v[38:39], v[40:41]
	s_nop 0
	v_add_f32_dpp v0, v0, v0 quad_perm:[2,3,0,1] row_mask:0xf bank_mask:0xf bound_ctrl:1
	v_add_f32_e32 v14, v38, v39
	s_nop 0
	v_add_f32_dpp v0, v0, v0 row_half_mirror row_mask:0xf bank_mask:0xf bound_ctrl:1
	s_nop 1
	v_add_f32_dpp v0, v0, v0 row_ror:8 row_mask:0xf bank_mask:0xf bound_ctrl:1
	s_waitcnt lgkmcnt(7)
	v_pk_fma_f32 v[2:3], v[34:35], v[0:1], v[6:7] op_sel_hi:[1,0,1] neg_lo:[1,0,0] neg_hi:[1,0,0]
	v_pk_fma_f32 v[4:5], v[36:37], v[0:1], v[4:5] op_sel_hi:[1,0,1] neg_lo:[1,0,0] neg_hi:[1,0,0]
	s_waitcnt lgkmcnt(2)
	v_pk_mul_f32 v[8:9], v[26:27], v[2:3]
	v_pk_mul_f32 v[6:7], v[48:49], v[4:5]
	v_pk_mul_f32 v[10:11], v[18:19], v[2:3]
	v_pk_mul_f32 v[12:13], v[20:21], v[4:5]
	v_pk_fma_f32 v[2:3], v[46:47], v[2:3], v[6:7]
	v_pk_fma_f32 v[4:5], v[28:29], v[4:5], v[8:9]
	v_add_f32_e32 v0, v2, v3
	v_add_f32_e32 v2, v4, v5
	ds_write2st64_b32 v88, v14, v0 offset0:220 offset1:224
	v_pk_fma_f32 v[8:9], v[86:87], v[24:25], v[12:13] op_sel_hi:[0,1,1]
	v_add_f32_dpp v0, v2, v2 quad_perm:[1,0,3,2] row_mask:0xf bank_mask:0xf bound_ctrl:1
	v_pk_fma_f32 v[6:7], v[86:87], v[22:23], v[10:11] op_sel_hi:[0,1,1]
	s_nop 0
	v_add_f32_dpp v0, v0, v0 quad_perm:[2,3,0,1] row_mask:0xf bank_mask:0xf bound_ctrl:1
	s_nop 1
	v_add_f32_dpp v0, v0, v0 row_half_mirror row_mask:0xf bank_mask:0xf bound_ctrl:1
	s_nop 1
	v_add_f32_dpp v0, v0, v0 row_ror:8 row_mask:0xf bank_mask:0xf bound_ctrl:1
	s_waitcnt lgkmcnt(2)
	v_pk_fma_f32 v[76:77], v[32:33], v[0:1], v[8:9] op_sel_hi:[1,0,1] neg_lo:[1,0,0] neg_hi:[1,0,0]
	v_pk_fma_f32 v[74:75], v[30:31], v[0:1], v[6:7] op_sel_hi:[1,0,1] neg_lo:[1,0,0] neg_hi:[1,0,0]
	s_waitcnt lgkmcnt(1)
	v_pk_mul_f32 v[2:3], v[52:53], v[76:77]
	s_nop 0
	v_pk_fma_f32 v[2:3], v[50:51], v[74:75], v[2:3]
	s_nop 0
	v_add_f32_e32 v0, v2, v3
	ds_write_b32 v88, v0 offset:58368
	s_waitcnt lgkmcnt(0)
	s_barrier
	s_cbranch_scc0 .LBB0_1050
	s_setprio 0

.LBB0_1102:
	v_ashrrev_i32_e32 v45, 31, v44
	v_lshlrev_b64 v[26:27], 1, v[44:45]
	v_or_b32_e32 v26, s37, v26
	v_readlane_b32 s2, v252, 0
	v_readlane_b32 s4, v252, 6
	v_or_b32_e32 v43, s61, v90
	v_sub_u32_e32 v46, s27, v90
	v_lshlrev_b64 v[30:31], 10, v[26:27]
	v_readlane_b32 s3, v252, 1
	v_lshlrev_b64 v[26:27], 9, v[26:27]
	v_readlane_b32 s5, v252, 7
	v_cndmask_b32_e64 v46, v46, v43, s[16:17]
	v_lshl_add_u64 v[28:29], s[2:3], 0, v[30:31]
	v_lshl_add_u64 v[26:27], s[4:5], 0, v[26:27]
	v_mov_b32_e32 v41, v1
	v_ashrrev_i32_e32 v47, 31, v46
	v_readlane_b32 s8, v252, 10
	v_lshl_add_u64 v[28:29], v[28:29], 0, v[0:1]
	v_lshl_add_u64 v[32:33], v[26:27], 0, v[40:41]
	v_readlane_b32 s10, v252, 20
	v_readlane_b32 s12, v252, 22
	v_readlane_b32 s6, v252, 8
	v_lshlrev_b64 v[46:47], 9, v[46:47]
	v_readlane_b32 s9, v252, 11
	global_load_dwordx4 v[26:29], v[28:29], off
	s_nop 0
	global_load_dwordx2 v[82:83], v[32:33], off
	v_lshlrev_b64 v[32:33], 10, v[44:45]
	v_readlane_b32 s11, v252, 21
	v_readlane_b32 s13, v252, 23
	v_lshlrev_b64 v[44:45], 9, v[44:45]
	v_readlane_b32 s7, v252, 9
	v_lshl_add_u64 v[46:47], s[8:9], 0, v[46:47]
	s_mov_b32 s27, s21
	v_lshl_add_u64 v[32:33], s[10:11], 0, v[32:33]
	v_lshl_add_u64 v[30:31], s[12:13], 0, v[30:31]
	v_lshl_add_u64 v[44:45], s[6:7], 0, v[44:45]
	v_lshl_add_u64 v[46:47], v[46:47], 0, s[26:27]
	s_mov_b32 s49, s21
	v_lshl_add_u64 v[32:33], v[32:33], 0, v[0:1]
	v_lshl_add_u64 v[34:35], v[30:31], 0, v[0:1]
	v_lshl_add_u64 v[44:45], v[44:45], 0, v[40:41]
	v_lshl_add_u64 v[46:47], v[46:47], 0, s[48:49]
	v_mov_b32_e32 v43, v1
	global_load_dwordx4 v[30:33], v[32:33], off
	s_nop 0
	global_load_dwordx4 v[34:37], v[34:35], off
	v_lshl_add_u64 v[46:47], v[46:47], 0, v[42:43]
	global_load_dwordx2 v[84:85], v[44:45], off
	global_load_dwordx2 v[86:87], v[46:47], off
	s_lshl_b32 s20, s37, 10
	v_lshl_add_u64 v[60:61], s[2:3], 0, v[0:1]
	s_add_u32 s2, s8, s26
	s_addc_u32 s3, s9, 0
	s_add_u32 s26, s2, s48
	s_addc_u32 s27, s3, 0
	v_readlane_b32 s2, v252, 14
	v_readlane_b32 s3, v252, 15
	s_add_u32 s2, s2, s20
	s_addc_u32 s3, s3, 0
	s_lshl_b32 s48, s60, 2
	s_add_u32 s2, s2, s48
	s_addc_u32 s3, s3, 0
	s_lshl_b32 s50, s33, 2
	s_waitcnt lgkmcnt(0)
	s_barrier
	v_lshl_add_u64 v[70:71], s[26:27], 0, v[42:43]
	s_add_u32 s26, s2, s50
	v_lshl_add_u64 v[64:65], s[10:11], 0, v[0:1]
	v_lshl_add_u64 v[66:67], s[12:13], 0, v[0:1]
	v_lshlrev_b32_e32 v0, 6, v39
	v_lshrrev_b32_e32 v94, 2, v39
	s_addc_u32 s27, s3, 0
	v_mov_b32_e32 v39, v1
	v_lshl_add_u64 v[62:63], s[4:5], 0, v[40:41]
	v_lshl_add_u64 v[68:69], s[6:7], 0, v[40:41]
	v_and_b32_e32 v93, 0xc0, v0
	v_add_u32_e32 v0, 0, v0
	v_lshl_add_u64 v[72:73], s[26:27], 0, v[38:39]
	s_sub_i32 s98, 1, s37
	s_sub_i32 s98, s98, s37
	s_ashr_i32 s99, s98, 31
	v_mov_b32_e32 v112, s98
	v_mov_b32_e32 v113, s99
	s_cmp_eq_u32 s37, 0
	s_cselect_b32 s98, 64, 0xbf
	s_add_i32 s98, s98, s25
	v_mov_b32_e32 v110, s98
	v_mad_i32_i24 v111, v55, v112, v110
	v_and_b32_e32 v108, 63, v232
	v_lshrrev_b32_e32 v108, 2, v108
	v_mad_i32_i24 v109, v108, v112, v110
	v_lshl_or_b32 v108, v111, 1, s37
	s_movk_i32 s98, 0x400
	s_movk_i32 s99, 0x200
	v_mad_u64_u32 v[96:97], vcc, v108, s98, v[60:61]
	v_mad_u64_u32 v[98:99], vcc, v108, s99, v[62:63]
	v_mad_u64_u32 v[100:101], vcc, v111, s98, v[64:65]
	v_mad_u64_u32 v[102:103], vcc, v108, s98, v[66:67]
	v_mad_u64_u32 v[104:105], vcc, v111, s99, v[68:69]
	v_mad_u64_u32 v[106:107], vcc, v109, s99, v[70:71]
	s_cmp_eq_u32 s37, 0
	s_cselect_b32 s98, 0, 0xff
	s_add_i32 s98, s98, s25
	v_mov_b32_e32 v110, s98
	v_mad_i32_i24 v111, v55, v112, v110
	s_movk_i32 s98, 0x800
	v_mad_u64_u32 v[108:109], vcc, v111, s98, v[72:73]
	s_sub_i32 s98, s24, s25
	s_movk_i32 s99, 0x1000
	s_cmp_eq_u32 s37, 0
	s_cselect_b32 s99, 0xffffff00, s99
	s_add_i32 s98, s98, s99
	s_lshl_b32 s98, s98, 9
	s_ashr_i32 s99, s98, 31
	v_mov_b32_e32 v120, s98
	v_mov_b32_e32 v121, s99
	s_lshl_b32 s98, s98, 1
	v_mov_b32_e32 v118, s98
	v_mov_b32_e32 v119, s99
	s_lshl_b32 s98, s98, 1
	v_mov_b32_e32 v110, s98
	v_mov_b32_e32 v111, s99
	v_lshlrev_b32_e32 v112, 15, v112
	v_ashrrev_i32_e32 v114, 1, v112
	v_mov_b32_e32 v115, v113
	v_ashrrev_i32_e32 v116, 2, v112
	v_mov_b32_e32 v117, v113
	s_mov_b32 s49, 0
	s_mov_b32 s51, 0
	s_branch .LBB0_1106

.LBB0_1104:
	s_waitcnt lgkmcnt(2)
	v_pk_add_f32 v[48:49], v[48:49], v[52:53]
	v_pk_add_f32 v[46:47], v[46:47], v[50:51]
	s_waitcnt lgkmcnt(0)
	v_pk_add_f32 v[40:41], v[40:41], v[44:45]
	v_pk_add_f32 v[38:39], v[38:39], v[42:43]
	v_pk_add_f32 v[40:41], v[48:49], v[40:41]
	v_pk_add_f32 v[38:39], v[46:47], v[38:39]
	v_pk_mov_b32 v[42:43], v[38:39], v[40:41] op_sel:[1,0]
	v_mov_b32_e32 v39, v41
	v_pk_add_f32 v[38:39], v[42:43], v[38:39]
	s_nop 0
	v_add_f32_e32 v40, v38, v39
	s_cmp_lg_u32 s49, 15
	s_cbranch_scc1 .Lscan_y_nofix
	v_lshl_add_u64 v[108:109], v[110:111], 0, v[108:109]
.Lscan_y_nofix:
	global_store_dword v[108:109], v40, off
	v_lshl_add_u64 v[108:109], v[112:113], 0, v[108:109]
	s_waitcnt lgkmcnt(0)
	s_barrier

.LBB0_1110:
	s_cmp_gt_u32 s49, 11
	s_cselect_b64 s[26:27], -1, 0
	s_cmp_lt_u32 s49, 12
	s_cselect_b64 s[46:47], -1, 0
	s_cmp_gt_i32 s51, 6
	s_cselect_b64 s[60:61], -1, 0
	s_or_b64 s[46:47], s[46:47], s[60:61]
	s_and_b64 vcc, exec, s[46:47]
	s_cbranch_vccnz .LBB0_1125
	s_add_i32 s2, s49, -12
	s_sub_i32 s3, 0x10b, s49
	s_cmpk_lt_u32 s49, 0x8c
	s_cselect_b32 s33, s2, s3
	s_cmp_lt_u32 s33, 24
	s_cbranch_scc1 .LBB0_1125
	s_lshl_b32 s2, s33, 3
	s_addk_i32 s2, 0xff47
	s_lshr_b32 s33, s2, 7
	s_cmp_gt_i32 s51, s33
	v_readlane_b32 s3, v250, 56
	s_cbranch_scc1 .LBB0_1124
.LBB0_1113:
	s_lshl_b32 s2, s51, 7
	s_sub_i32 s2, 0x340, s2
	s_cmp_gt_i32 s51, 5
	s_cselect_b32 s71, s2, 0x80
	s_lshl_b32 s46, s51, 6
	s_ashr_i32 s47, s46, 31
	s_lshl_b64 s[46:47], s[46:47], 2
	s_add_u32 s46, s3, s46
	v_readlane_b32 s2, v250, 57
	s_addc_u32 s47, s2, s47
	s_mov_b32 s73, 0x400001
	s_branch .LBB0_1115

.LBB0_1125:
	s_cmp_lg_u32 s49, 12
	s_cbranch_scc1 .Lscan_ld_nofix
	v_lshl_add_u64 v[96:97], v[110:111], 0, v[96:97]
	v_lshl_add_u64 v[98:99], v[118:119], 0, v[98:99]
	v_lshl_add_u64 v[100:101], v[118:119], 0, v[100:101]
	v_lshl_add_u64 v[102:103], v[110:111], 0, v[102:103]
	v_lshl_add_u64 v[104:105], v[120:121], 0, v[104:105]
	v_lshl_add_u64 v[106:107], v[120:121], 0, v[106:107]
.Lscan_ld_nofix:
	global_load_dwordx4 v[2:5], v[96:97], off
	global_load_dwordx2 v[56:57], v[98:99], off
	global_load_dwordx4 v[6:9], v[100:101], off
	global_load_dwordx4 v[10:13], v[102:103], off
	global_load_dwordx2 v[58:59], v[104:105], off
	global_load_dwordx2 v[74:75], v[106:107], off
	v_lshl_add_u64 v[96:97], v[112:113], 0, v[96:97]
	v_lshl_add_u64 v[98:99], v[114:115], 0, v[98:99]
	v_lshl_add_u64 v[100:101], v[114:115], 0, v[100:101]
	v_lshl_add_u64 v[102:103], v[112:113], 0, v[102:103]
	v_lshl_add_u64 v[104:105], v[116:117], 0, v[104:105]
	v_lshl_add_u64 v[106:107], v[116:117], 0, v[106:107]
	s_mov_b64 s[76:77], s[40:41]
	s_cmp_eq_u32 s49, 0
	s_cbranch_scc1 .LBB0_1162

.LBB0_1161:
	s_waitcnt lgkmcnt(2)
	v_pk_add_f32 v[48:49], v[48:49], v[52:53]
	v_pk_add_f32 v[46:47], v[46:47], v[50:51]
	s_waitcnt lgkmcnt(0)
	v_pk_add_f32 v[40:41], v[40:41], v[44:45]
	v_pk_add_f32 v[38:39], v[38:39], v[42:43]
	v_pk_add_f32 v[40:41], v[48:49], v[40:41]
	v_pk_add_f32 v[38:39], v[46:47], v[38:39]
	v_pk_mov_b32 v[42:43], v[38:39], v[40:41] op_sel:[1,0]
	v_mov_b32_e32 v39, v41
	v_pk_add_f32 v[38:39], v[42:43], v[38:39]
	s_nop 0
	v_add_f32_e32 v40, v38, v39
	global_store_dword v[108:109], v40, off
	v_lshl_add_u64 v[108:109], v[112:113], 0, v[108:109]

.LBB0_1169:
	s_cmp_gt_u32 s49, 10
	s_cselect_b64 s[26:27], -1, 0
	s_cmp_lt_u32 s49, 11
	s_cselect_b64 s[46:47], -1, 0
	s_cmp_gt_i32 s51, 6
	s_cselect_b64 s[76:77], -1, 0
	s_or_b64 s[46:47], s[46:47], s[76:77]
	s_and_b64 vcc, exec, s[46:47]
	s_cbranch_vccnz .LBB0_1182
	s_add_i32 s2, s49, -11
	s_sub_i32 s3, 0x10a, s49
	s_cmpk_lt_u32 s49, 0x8b
	s_cselect_b32 s33, s2, s3
	s_cmp_lt_u32 s33, 24
	s_cbranch_scc1 .LBB0_1182
	s_lshl_b32 s2, s33, 3
	s_addk_i32 s2, 0xff47
	s_lshr_b32 s33, s2, 7
	s_cmp_gt_i32 s51, s33
	v_readlane_b32 s3, v250, 56
	s_mov_b64 s[76:77], s[40:41]
	s_cbranch_scc1 .LBB0_1184

.LBB0_1185:
	global_load_dwordx4 v[14:17], v[96:97], off
	global_load_dwordx2 v[76:77], v[98:99], off
	global_load_dwordx4 v[18:21], v[100:101], off
	global_load_dwordx4 v[22:25], v[102:103], off
	global_load_dwordx2 v[78:79], v[104:105], off
	global_load_dwordx2 v[80:81], v[106:107], off
	v_lshl_add_u64 v[96:97], v[112:113], 0, v[96:97]
	v_lshl_add_u64 v[98:99], v[114:115], 0, v[98:99]
	v_lshl_add_u64 v[100:101], v[114:115], 0, v[100:101]
	v_lshl_add_u64 v[102:103], v[112:113], 0, v[102:103]
	v_lshl_add_u64 v[104:105], v[116:117], 0, v[104:105]
	v_lshl_add_u64 v[106:107], v[116:117], 0, v[106:107]
	s_movk_i32 s79, 0x4400
	v_readlane_b32 s78, v249, 35
	s_mov_b64 s[76:77], s[40:41]
	v_readlane_b32 s71, v250, 15

.LBB0_1221:
	s_waitcnt lgkmcnt(2)
	v_pk_add_f32 v[48:49], v[48:49], v[52:53]
	v_pk_add_f32 v[46:47], v[46:47], v[50:51]
	s_waitcnt lgkmcnt(0)
	v_pk_add_f32 v[40:41], v[40:41], v[44:45]
	v_pk_add_f32 v[38:39], v[38:39], v[42:43]
	v_pk_add_f32 v[40:41], v[48:49], v[40:41]
	v_pk_add_f32 v[38:39], v[46:47], v[38:39]
	v_pk_mov_b32 v[42:43], v[38:39], v[40:41] op_sel:[1,0]
	v_mov_b32_e32 v39, v41
	v_pk_add_f32 v[38:39], v[42:43], v[38:39]
	s_andn2_b64 vcc, exec, s[60:61]
	v_add_f32_e32 v40, v38, v39
	global_store_dword v[108:109], v40, off
	v_lshl_add_u64 v[108:109], v[112:113], 0, v[108:109]
	s_waitcnt lgkmcnt(0)
	s_barrier
	s_cmpk_lt_u32 s49, 6
	s_cbranch_scc1 .Lscan_ld_drain_c
	s_cmpk_lt_u32 s49, 0x109
	s_cbranch_scc1 .Lscan_ld_steady_c

.LBB0_1226:
	s_cmpk_gt_u32 s49, 0x109
	s_cbranch_scc1 .LBB0_1266
	s_cmp_gt_u32 s49, 9
	s_cselect_b64 s[26:27], -1, 0
	s_cmp_lt_u32 s49, 10
	s_cselect_b64 s[46:47], -1, 0
	s_cmp_gt_i32 s51, 6
	s_cselect_b64 s[60:61], -1, 0
	s_or_b64 s[46:47], s[46:47], s[60:61]
	s_and_b64 vcc, exec, s[46:47]
	s_cbranch_vccnz .LBB0_1242
	s_add_i32 s2, s49, -10
	s_sub_i32 s3, 0x109, s49
	s_cmpk_lt_u32 s49, 0x8a
	s_cselect_b32 s33, s2, s3
	s_cmp_lt_u32 s33, 24
	s_cbranch_scc1 .LBB0_1242
	s_lshl_b32 s2, s33, 3
	s_addk_i32 s2, 0xff47
	s_lshr_b32 s33, s2, 7
	s_cmp_gt_i32 s51, s33
	v_readlane_b32 s3, v250, 56
	s_cbranch_scc1 .LBB0_1241
.LBB0_1230:
	s_lshl_b32 s2, s51, 7
	s_sub_i32 s2, 0x340, s2
	s_cmp_gt_i32 s51, 5
	s_cselect_b32 s71, s2, 0x80
	s_lshl_b32 s46, s51, 6
	s_ashr_i32 s47, s46, 31
	s_lshl_b64 s[46:47], s[46:47], 2
	s_add_u32 s46, s3, s46
	v_readlane_b32 s2, v250, 57
	s_addc_u32 s47, s2, s47
	s_mov_b32 s72, 0x400001
	s_branch .LBB0_1232

.LBB0_1242:
	global_load_dwordx4 v[26:29], v[96:97], off
	global_load_dwordx2 v[82:83], v[98:99], off
	global_load_dwordx4 v[30:33], v[100:101], off
	global_load_dwordx4 v[34:37], v[102:103], off
	global_load_dwordx2 v[84:85], v[104:105], off
	global_load_dwordx2 v[86:87], v[106:107], off
	v_lshl_add_u64 v[96:97], v[112:113], 0, v[96:97]
	v_lshl_add_u64 v[98:99], v[114:115], 0, v[98:99]
	v_lshl_add_u64 v[100:101], v[114:115], 0, v[100:101]
	v_lshl_add_u64 v[102:103], v[112:113], 0, v[102:103]
	v_lshl_add_u64 v[104:105], v[116:117], 0, v[104:105]
	v_lshl_add_u64 v[106:107], v[116:117], 0, v[106:107]
	v_readlane_b32 s73, v250, 16
	s_mov_b64 s[76:77], s[40:41]
.LBB0_1266:
	s_add_i32 s2, s49, 1
	s_lshl_b32 s3, s2, 14
	s_and_b32 s3, s3, 0x4000
	v_add_u32_e32 v42, s3, v0
	ds_read_b128 v[46:49], v42 offset:43008
	ds_read_b128 v[50:53], v42 offset:43024
	ds_read_b128 v[38:41], v42 offset:43040
	ds_read_b128 v[42:45], v42 offset:43056
	s_branch .LBB0_1104

.LBB0_1280:
	s_andn2_b64 vcc, exec, s[24:25]
	s_cbranch_vccnz .LBB0_2065
	v_readlane_b32 s2, v250, 24
	s_cmp_gt_i32 s2, 0
	s_mov_b64 s[24:25], -1
	s_cbranch_scc0 .LBB0_1949
	s_cmpk_gt_i32 s30, 0xff
	s_cbranch_scc1 .LBB0_1948
	s_cmp_gt_i32 s30, 63
	s_cbranch_scc0 .LBB0_1285
	s_sub_i32 s2, s30, 64
	s_lshr_b32 s2, s2, 3
	s_lshl_b32 s3, s30, 8
	s_and_b32 s3, s3, 0x300
	s_and_b32 s24, s30, 4
	s_sub_i32 s25, 0xff, s2
	s_cmp_eq_u32 s24, 0
	s_cselect_b32 s2, s2, s25
	s_add_i32 s26, s2, s3
	s_mov_b64 s[24:25], 0

.LBB0_1544:
	s_add_i32 s31, s31, s36
	s_cmpk_gt_i32 s31, 0xff
	s_cselect_b64 s[24:25], -1, 0
	s_mov_b32 s37, -1
	s_and_b64 vcc, exec, s[24:25]
	s_cbranch_vccnz .LBB0_1549
	s_cmp_gt_i32 s31, 63
	s_mov_b64 s[26:27], -1
	s_cbranch_scc0 .LBB0_1547
	s_sub_i32 s2, s31, 64
	s_lshr_b32 s2, s2, 3
	s_lshl_b32 s3, s31, 8
	s_and_b32 s3, s3, 0x300
	s_and_b32 s26, s31, 4
	s_sub_i32 s27, 0xff, s2
	s_cmp_eq_u32 s26, 0
	s_cselect_b32 s2, s2, s27
	s_add_i32 s37, s2, s3
	s_mov_b64 s[26:27], 0
